# adds: windowed-attention fast path - tiles fully inside the window skip per-element window compares/selects
# baseline (speedup 1.0000x reference)
.LBB0_377:
	s_bitcmp1_b32 s26, 0
	s_cselect_b32 s26, 0x5400, 0
	s_add_i32 s27, s26, 0
	v_add_u32_e32 v0, s27, v226
	ds_read_b128 v[194:197], v0 offset:0
	ds_read_b128 v[198:201], v0 offset:4608
	ds_read_b128 v[190:193], v0 offset:32
	ds_read_b128 v[186:189], v0 offset:4640
	ds_read_b128 v[182:185], v0 offset:64
	ds_read_b128 v[178:181], v0 offset:4672
	ds_read_b128 v[174:177], v0 offset:96
	ds_read_b128 v[170:173], v0 offset:4704
	v_add_u32_e32 v0, s27, v227
	ds_read_b64_tr_b16 v[166:167], v0 offset:0
	ds_read_b64_tr_b16 v[168:169], v0 offset:1536
	ds_read_b64_tr_b16 v[162:163], v0 offset:64
	ds_read_b64_tr_b16 v[164:165], v0 offset:1600
	ds_read_b64_tr_b16 v[158:159], v0 offset:3072
	ds_read_b64_tr_b16 v[160:161], v0 offset:4608
	ds_read_b64_tr_b16 v[154:155], v0 offset:3136
	ds_read_b64_tr_b16 v[156:157], v0 offset:4672
	ds_read_b64_tr_b16 v[150:151], v0 offset:6144
	ds_read_b64_tr_b16 v[152:153], v0 offset:7680
	ds_read_b64_tr_b16 v[146:147], v0 offset:6208
	ds_read_b64_tr_b16 v[148:149], v0 offset:7744
	ds_read_b64_tr_b16 v[142:143], v0 offset:9216
	ds_read_b64_tr_b16 v[144:145], v0 offset:10752
	ds_read_b64_tr_b16 v[138:139], v0 offset:9280
	ds_read_b64_tr_b16 v[140:141], v0 offset:10816
	s_waitcnt lgkmcnt(0)
	s_sub_i32 s27, s24, 63
	s_cmp_lt_u32 s24, s5
	s_cselect_b64 s[30:31], -1, 0
	s_cmp_gt_u32 s27, s21
	s_cselect_b64 s[38:39], -1, 0
	s_or_b64 s[30:31], s[30:31], s[38:39]
	v_add_u32_e32 v233, s24, v229
	s_and_b64 vcc, exec, s[30:31]
	v_subrev_u32_e32 v245, 63, v233
	v_subrev_u32_e32 v244, 62, v233
	v_subrev_u32_e32 v243, 61, v233
	v_subrev_u32_e32 v242, 60, v233
	v_subrev_u32_e32 v241, 55, v233
	v_subrev_u32_e32 v240, 54, v233
	v_subrev_u32_e32 v239, 53, v233
	v_subrev_u32_e32 v238, 52, v233
	v_subrev_u32_e32 v237, 47, v233
	v_subrev_u32_e32 v236, 46, v233
	v_subrev_u32_e32 v235, 45, v233
	v_subrev_u32_e32 v234, 44, v233
	v_subrev_u32_e32 v232, 39, v233
	v_subrev_u32_e32 v231, 38, v233
	v_subrev_u32_e32 v230, 37, v233
	v_subrev_u32_e32 v0, 36, v233
	s_cbranch_vccnz .LBB0_379
	s_sub_i32 s30, s27, s5
	s_sub_i32 s30, s30, 31
	s_cmp_le_u32 s30, 0xa2
	s_cbranch_scc1 .Lswa_fast0
	v_mfma_f32_32x32x16_bf16 v[82:97], v[194:197], v[98:101], 0
	v_subrev_u32_e32 v202, 31, v233
	v_cmp_gt_u32_e32 vcc, s96, v245
	v_mfma_f32_32x32x16_bf16 v[66:81], v[198:201], v[98:101], 0
	v_mfma_f32_32x32x16_bf16 v[82:97], v[190:193], v[102:105], v[82:97]
	v_mfma_f32_32x32x16_bf16 v[66:81], v[186:189], v[102:105], v[66:81]
	v_mfma_f32_32x32x16_bf16 v[82:97], v[182:185], v[106:109], v[82:97]
	v_mfma_f32_32x32x16_bf16 v[66:81], v[178:181], v[106:109], v[66:81]
	v_mfma_f32_32x32x16_bf16 v[82:97], v[174:177], v[110:113], v[82:97]
	v_mfma_f32_32x32x16_bf16 v[66:81], v[170:173], v[110:113], v[66:81]
	s_nop 10
	v_sub_f32_e32 v82, v82, v223
	v_exp_f32_e32 v82, v82
	v_sub_f32_e32 v83, v83, v223
	v_exp_f32_e32 v83, v83
	v_cndmask_b32_e32 v203, 0, v82, vcc
	v_cmp_gt_u32_e32 vcc, s96, v202
	v_sub_f32_e32 v66, v66, v223
	v_exp_f32_e32 v66, v66
	v_sub_f32_e32 v67, v67, v223
	v_exp_f32_e32 v67, v67
	v_subrev_u32_e32 v82, 30, v233
	v_cndmask_b32_e32 v202, 0, v66, vcc
	v_cmp_gt_u32_e32 vcc, s96, v244
	v_sub_f32_e32 v68, v68, v223
	v_add_f32_e32 v66, v203, v202
	v_cndmask_b32_e32 v204, 0, v83, vcc
	v_cmp_gt_u32_e32 vcc, s96, v82
	v_sub_f32_e32 v82, v84, v223
	v_exp_f32_e32 v82, v82
	v_cndmask_b32_e32 v205, 0, v67, vcc
	v_exp_f32_e32 v68, v68
	v_add_f32_e32 v66, 0, v66
	v_add_f32_e32 v67, v204, v205
	v_add_f32_e32 v66, v67, v66
	v_subrev_u32_e32 v67, 29, v233
	v_cmp_gt_u32_e32 vcc, s96, v243
	v_sub_f32_e32 v69, v69, v223
	v_exp_f32_e32 v69, v69
	v_cndmask_b32_e32 v212, 0, v82, vcc
	v_cmp_gt_u32_e32 vcc, s96, v67
	v_sub_f32_e32 v78, v78, v223
	s_nop 0
	v_cndmask_b32_e32 v213, 0, v68, vcc
	v_sub_f32_e32 v68, v85, v223
	v_exp_f32_e32 v68, v68
	v_add_f32_e32 v67, v212, v213
	v_add_f32_e32 v66, v67, v66
	v_subrev_u32_e32 v67, 28, v233
	v_cmp_gt_u32_e32 vcc, s96, v242
	s_nop 1
	v_cndmask_b32_e32 v216, 0, v68, vcc
	v_cmp_gt_u32_e32 vcc, s96, v67
	s_nop 1
	v_cndmask_b32_e32 v217, 0, v69, vcc
	v_add_f32_e32 v67, v216, v217
	v_add_f32_e32 v82, v67, v66
	v_sub_f32_e32 v66, v86, v223
	v_sub_f32_e32 v67, v70, v223
	v_exp_f32_e32 v66, v66
	v_exp_f32_e32 v68, v67
	v_sub_f32_e32 v67, v87, v223
	v_exp_f32_e32 v69, v67
	v_sub_f32_e32 v67, v71, v223
	v_cmp_gt_u32_e32 vcc, s96, v241
	v_exp_f32_e32 v70, v67
	v_subrev_u32_e32 v71, 22, v233
	v_cndmask_b32_e32 v67, 0, v66, vcc
	v_cmp_gt_u32_e32 vcc, s96, v240
	s_nop 1
	v_cndmask_b32_e32 v66, 0, v69, vcc
	v_subrev_u32_e32 v69, 23, v233
	v_cmp_gt_u32_e32 vcc, s96, v69
	s_nop 1
	v_cndmask_b32_e32 v69, 0, v68, vcc
	v_cmp_gt_u32_e32 vcc, s96, v71
	s_nop 1
	v_cndmask_b32_e32 v68, 0, v70, vcc
	v_pk_add_f32 v[70:71], v[66:67], v[68:69]
	v_pk_mov_b32 v[84:85], v[68:69], v[68:69] op_sel:[1,0]
	v_add_f32_e32 v71, v71, v82
	v_pk_mov_b32 v[82:83], v[66:67], v[66:67] op_sel:[1,0]
	v_sub_f32_e32 v66, v88, v223
	v_sub_f32_e32 v67, v72, v223
	v_exp_f32_e32 v66, v66
	v_exp_f32_e32 v68, v67
	v_sub_f32_e32 v67, v89, v223
	v_exp_f32_e32 v69, v67
	v_sub_f32_e32 v67, v73, v223
	v_cmp_gt_u32_e32 vcc, s96, v239
	v_add_f32_e32 v86, v70, v71
	v_exp_f32_e32 v70, v67
	v_cndmask_b32_e32 v67, 0, v66, vcc
	v_cmp_gt_u32_e32 vcc, s96, v238
	v_subrev_u32_e32 v71, 20, v233
	s_nop 0
	v_cndmask_b32_e32 v66, 0, v69, vcc
	v_subrev_u32_e32 v69, 21, v233
	v_cmp_gt_u32_e32 vcc, s96, v69
	v_pk_mov_b32 v[72:73], v[66:67], v[66:67] op_sel:[1,0]
	s_nop 0
	v_cndmask_b32_e32 v69, 0, v68, vcc
	v_cmp_gt_u32_e32 vcc, s96, v71
	s_nop 1
	v_cndmask_b32_e32 v68, 0, v70, vcc
	v_pk_add_f32 v[70:71], v[66:67], v[68:69]
	v_sub_f32_e32 v66, v90, v223
	v_sub_f32_e32 v67, v74, v223
	v_add_f32_e32 v71, v71, v86
	v_pk_mov_b32 v[86:87], v[68:69], v[68:69] op_sel:[1,0]
	v_exp_f32_e32 v66, v66
	v_exp_f32_e32 v68, v67
	v_sub_f32_e32 v67, v91, v223
	v_exp_f32_e32 v69, v67
	v_sub_f32_e32 v67, v75, v223
	v_cmp_gt_u32_e32 vcc, s96, v237
	v_add_f32_e32 v88, v70, v71
	v_exp_f32_e32 v70, v67
	v_cndmask_b32_e32 v67, 0, v66, vcc
	v_cmp_gt_u32_e32 vcc, s96, v236
	v_add_u32_e32 v71, -14, v233
	s_nop 0
	v_cndmask_b32_e32 v66, 0, v69, vcc
	v_add_u32_e32 v69, -15, v233
	v_cmp_gt_u32_e32 vcc, s96, v69
	v_pk_mov_b32 v[74:75], v[66:67], v[66:67] op_sel:[1,0]
	s_nop 0
	v_cndmask_b32_e32 v69, 0, v68, vcc
	v_cmp_gt_u32_e32 vcc, s96, v71
	s_nop 1
	v_cndmask_b32_e32 v68, 0, v70, vcc
	v_pk_add_f32 v[70:71], v[66:67], v[68:69]
	v_sub_f32_e32 v66, v92, v223
	v_sub_f32_e32 v67, v76, v223
	v_add_f32_e32 v71, v71, v88
	v_pk_mov_b32 v[88:89], v[68:69], v[68:69] op_sel:[1,0]
	v_exp_f32_e32 v66, v66
	v_exp_f32_e32 v68, v67
	v_sub_f32_e32 v67, v93, v223
	v_exp_f32_e32 v69, v67
	v_sub_f32_e32 v67, v77, v223
	v_cmp_gt_u32_e32 vcc, s96, v235
	v_add_f32_e32 v90, v70, v71
	v_exp_f32_e32 v70, v67
	v_cndmask_b32_e32 v67, 0, v66, vcc
	v_cmp_gt_u32_e32 vcc, s96, v234
	v_add_u32_e32 v71, -12, v233
	s_nop 0
	v_cndmask_b32_e32 v66, 0, v69, vcc
	v_add_u32_e32 v69, -13, v233
	v_cmp_gt_u32_e32 vcc, s96, v69
	v_pk_mov_b32 v[76:77], v[66:67], v[66:67] op_sel:[1,0]
	s_nop 0
	v_cndmask_b32_e32 v69, 0, v68, vcc
	v_cmp_gt_u32_e32 vcc, s96, v71
	s_nop 1
	v_cndmask_b32_e32 v68, 0, v70, vcc
	v_pk_add_f32 v[70:71], v[66:67], v[68:69]
	v_sub_f32_e32 v66, v94, v223
	v_exp_f32_e32 v66, v66
	v_sub_f32_e32 v67, v95, v223
	v_exp_f32_e32 v67, v67
	v_add_f32_e32 v71, v71, v90
	v_cmp_gt_u32_e32 vcc, s96, v232
	v_add_f32_e32 v218, v70, v71
	v_pk_mov_b32 v[90:91], v[68:69], v[68:69] op_sel:[1,0]
	v_cndmask_b32_e32 v71, 0, v66, vcc
	v_cmp_gt_u32_e32 vcc, s96, v231
	v_cvt_pk_bf16_f32 v66, v203, v204
	v_cvt_pk_bf16_f32 v68, v82, v83
	v_cndmask_b32_e32 v70, 0, v67, vcc
	v_cvt_pk_bf16_f32 v67, v212, v216
	v_cvt_pk_bf16_f32 v69, v72, v73
	v_sub_f32_e32 v82, v96, v223
	v_exp_f32_e32 v82, v82
	v_mfma_f32_32x32x16_bf16 v[50:65], v[166:169], v[66:69], v[50:65]
	v_sub_f32_e32 v83, v97, v223
	v_exp_f32_e32 v92, v83
	v_cmp_gt_u32_e32 vcc, s96, v230
	v_pk_mov_b32 v[72:73], v[70:71], v[70:71] op_sel:[1,0]
	s_nop 0
	v_cndmask_b32_e32 v83, 0, v82, vcc
	v_cmp_gt_u32_e32 vcc, s96, v0
	v_mfma_f32_32x32x16_bf16 v[34:49], v[162:165], v[66:69], v[34:49]
	v_cvt_pk_bf16_f32 v66, v74, v75
	v_cndmask_b32_e32 v82, 0, v92, vcc
	v_pk_mov_b32 v[92:93], v[82:83], v[82:83] op_sel:[1,0]
	v_cvt_pk_bf16_f32 v67, v76, v77
	v_cvt_pk_bf16_f32 v68, v72, v73
	v_cvt_pk_bf16_f32 v69, v92, v93
	v_exp_f32_e32 v72, v78
	v_sub_f32_e32 v73, v79, v223
	v_mfma_f32_32x32x16_bf16 v[50:65], v[158:161], v[66:69], v[50:65]
	v_exp_f32_e32 v74, v73
	v_sub_f32_e32 v76, v80, v223
	v_add_u32_e32 v73, -7, v233
	v_exp_f32_e32 v76, v76
	v_sub_f32_e32 v77, v81, v223
	v_add_u32_e32 v75, -6, v233
	v_cmp_gt_u32_e32 vcc, s96, v73
	v_mfma_f32_32x32x16_bf16 v[34:49], v[154:157], v[66:69], v[34:49]
	v_cvt_pk_bf16_f32 v66, v202, v205
	v_cvt_pk_bf16_f32 v67, v213, v217
	v_cvt_pk_bf16_f32 v68, v84, v85
	v_cvt_pk_bf16_f32 v69, v86, v87
	v_exp_f32_e32 v78, v77
	v_cndmask_b32_e32 v73, 0, v72, vcc
	v_cmp_gt_u32_e32 vcc, s96, v75
	v_mfma_f32_32x32x16_bf16 v[50:65], v[150:153], v[66:69], v[50:65]
	v_add_u32_e32 v77, -5, v233
	v_cndmask_b32_e32 v72, 0, v74, vcc
	v_add_u32_e32 v79, -4, v233
	v_cmp_gt_u32_e32 vcc, s96, v77
	v_pk_mov_b32 v[74:75], v[72:73], v[72:73] op_sel:[1,0]
	v_pk_add_f32 v[70:71], v[70:71], v[72:73]
	v_cndmask_b32_e32 v77, 0, v76, vcc
	v_mfma_f32_32x32x16_bf16 v[34:49], v[146:149], v[66:69], v[34:49]
	v_cmp_gt_u32_e32 vcc, s96, v79
	v_cvt_pk_bf16_f32 v66, v88, v89
	v_cvt_pk_bf16_f32 v67, v90, v91
	v_cndmask_b32_e32 v76, 0, v78, vcc
	v_pk_mov_b32 v[78:79], v[76:77], v[76:77] op_sel:[1,0]
	v_cvt_pk_bf16_f32 v68, v74, v75
	v_cvt_pk_bf16_f32 v69, v78, v79
	v_add_f32_e32 v71, v71, v218
	v_add_f32_e32 v72, v70, v71
	v_mfma_f32_32x32x16_bf16 v[50:65], v[142:145], v[66:69], v[50:65]
	v_add_f32_e64 v70, v82, v76
	v_add_f32_e64 v71, v83, v77
	v_add_f32_e32 v71, v71, v72
	v_add_f32_e32 v70, v70, v71
	v_add_f32_e32 v228, v228, v70
	v_mfma_f32_32x32x16_bf16 v[34:49], v[138:141], v[66:69], v[34:49]
	s_branch .LBB0_379
.Lswa_fast0:
	v_mfma_f32_32x32x16_bf16 v[82:97], v[194:197], v[98:101], 0
	v_mfma_f32_32x32x16_bf16 v[66:81], v[198:201], v[98:101], 0
	v_mfma_f32_32x32x16_bf16 v[82:97], v[190:193], v[102:105], v[82:97]
	v_mfma_f32_32x32x16_bf16 v[66:81], v[186:189], v[102:105], v[66:81]
	v_mfma_f32_32x32x16_bf16 v[82:97], v[182:185], v[106:109], v[82:97]
	v_mfma_f32_32x32x16_bf16 v[66:81], v[178:181], v[106:109], v[66:81]
	v_mfma_f32_32x32x16_bf16 v[82:97], v[174:177], v[110:113], v[82:97]
	v_mfma_f32_32x32x16_bf16 v[66:81], v[170:173], v[110:113], v[66:81]
	s_nop 10
	v_sub_f32_e32 v82, v82, v223
	v_exp_f32_e32 v82, v82
	v_sub_f32_e32 v83, v83, v223
	v_exp_f32_e32 v83, v83
	v_mov_b32_e32 v203, v82
	v_sub_f32_e32 v66, v66, v223
	v_exp_f32_e32 v66, v66
	v_sub_f32_e32 v67, v67, v223
	v_exp_f32_e32 v67, v67
	v_mov_b32_e32 v202, v66
	v_sub_f32_e32 v68, v68, v223
	v_add_f32_e32 v66, v203, v202
	v_mov_b32_e32 v204, v83
	v_sub_f32_e32 v82, v84, v223
	v_exp_f32_e32 v82, v82
	v_mov_b32_e32 v205, v67
	v_exp_f32_e32 v68, v68
	v_add_f32_e32 v66, 0, v66
	v_add_f32_e32 v67, v204, v205
	v_add_f32_e32 v66, v67, v66
	v_sub_f32_e32 v69, v69, v223
	v_exp_f32_e32 v69, v69
	v_mov_b32_e32 v212, v82
	v_sub_f32_e32 v78, v78, v223
	v_mov_b32_e32 v213, v68
	v_sub_f32_e32 v68, v85, v223
	v_exp_f32_e32 v68, v68
	v_add_f32_e32 v67, v212, v213
	v_add_f32_e32 v66, v67, v66
	v_mov_b32_e32 v216, v68
	v_mov_b32_e32 v217, v69
	v_add_f32_e32 v67, v216, v217
	v_add_f32_e32 v82, v67, v66
	v_sub_f32_e32 v66, v86, v223
	v_sub_f32_e32 v67, v70, v223
	v_exp_f32_e32 v66, v66
	v_exp_f32_e32 v68, v67
	v_sub_f32_e32 v67, v87, v223
	v_exp_f32_e32 v69, v67
	v_sub_f32_e32 v67, v71, v223
	v_exp_f32_e32 v70, v67
	v_mov_b32_e32 v67, v66
	v_mov_b32_e32 v66, v69
	v_mov_b32_e32 v69, v68
	v_mov_b32_e32 v68, v70
	v_pk_add_f32 v[70:71], v[66:67], v[68:69]
	v_pk_mov_b32 v[84:85], v[68:69], v[68:69] op_sel:[1,0]
	v_add_f32_e32 v71, v71, v82
	v_pk_mov_b32 v[82:83], v[66:67], v[66:67] op_sel:[1,0]
	v_sub_f32_e32 v66, v88, v223
	v_sub_f32_e32 v67, v72, v223
	v_exp_f32_e32 v66, v66
	v_exp_f32_e32 v68, v67
	v_sub_f32_e32 v67, v89, v223
	v_exp_f32_e32 v69, v67
	v_sub_f32_e32 v67, v73, v223
	v_add_f32_e32 v86, v70, v71
	v_exp_f32_e32 v70, v67
	v_mov_b32_e32 v67, v66
	v_mov_b32_e32 v66, v69
	v_pk_mov_b32 v[72:73], v[66:67], v[66:67] op_sel:[1,0]
	v_mov_b32_e32 v69, v68
	v_mov_b32_e32 v68, v70
	v_pk_add_f32 v[70:71], v[66:67], v[68:69]
	v_sub_f32_e32 v66, v90, v223
	v_sub_f32_e32 v67, v74, v223
	v_add_f32_e32 v71, v71, v86
	v_pk_mov_b32 v[86:87], v[68:69], v[68:69] op_sel:[1,0]
	v_exp_f32_e32 v66, v66
	v_exp_f32_e32 v68, v67
	v_sub_f32_e32 v67, v91, v223
	v_exp_f32_e32 v69, v67
	v_sub_f32_e32 v67, v75, v223
	v_add_f32_e32 v88, v70, v71
	v_exp_f32_e32 v70, v67
	v_mov_b32_e32 v67, v66
	v_mov_b32_e32 v66, v69
	v_pk_mov_b32 v[74:75], v[66:67], v[66:67] op_sel:[1,0]
	v_mov_b32_e32 v69, v68
	v_mov_b32_e32 v68, v70
	v_pk_add_f32 v[70:71], v[66:67], v[68:69]
	v_sub_f32_e32 v66, v92, v223
	v_sub_f32_e32 v67, v76, v223
	v_add_f32_e32 v71, v71, v88
	v_pk_mov_b32 v[88:89], v[68:69], v[68:69] op_sel:[1,0]
	v_exp_f32_e32 v66, v66
	v_exp_f32_e32 v68, v67
	v_sub_f32_e32 v67, v93, v223
	v_exp_f32_e32 v69, v67
	v_sub_f32_e32 v67, v77, v223
	v_add_f32_e32 v90, v70, v71
	v_exp_f32_e32 v70, v67
	v_mov_b32_e32 v67, v66
	v_mov_b32_e32 v66, v69
	v_pk_mov_b32 v[76:77], v[66:67], v[66:67] op_sel:[1,0]
	v_mov_b32_e32 v69, v68
	v_mov_b32_e32 v68, v70
	v_pk_add_f32 v[70:71], v[66:67], v[68:69]
	v_sub_f32_e32 v66, v94, v223
	v_exp_f32_e32 v66, v66
	v_sub_f32_e32 v67, v95, v223
	v_exp_f32_e32 v67, v67
	v_add_f32_e32 v71, v71, v90
	v_add_f32_e32 v218, v70, v71
	v_pk_mov_b32 v[90:91], v[68:69], v[68:69] op_sel:[1,0]
	v_mov_b32_e32 v71, v66
	v_cvt_pk_bf16_f32 v66, v203, v204
	v_cvt_pk_bf16_f32 v68, v82, v83
	v_mov_b32_e32 v70, v67
	v_cvt_pk_bf16_f32 v67, v212, v216
	v_cvt_pk_bf16_f32 v69, v72, v73
	v_sub_f32_e32 v82, v96, v223
	v_exp_f32_e32 v82, v82
	v_mfma_f32_32x32x16_bf16 v[50:65], v[166:169], v[66:69], v[50:65]
	v_sub_f32_e32 v83, v97, v223
	v_exp_f32_e32 v92, v83
	v_pk_mov_b32 v[72:73], v[70:71], v[70:71] op_sel:[1,0]
	v_mov_b32_e32 v83, v82
	v_mfma_f32_32x32x16_bf16 v[34:49], v[162:165], v[66:69], v[34:49]
	v_cvt_pk_bf16_f32 v66, v74, v75
	v_mov_b32_e32 v82, v92
	v_pk_mov_b32 v[92:93], v[82:83], v[82:83] op_sel:[1,0]
	v_cvt_pk_bf16_f32 v67, v76, v77
	v_cvt_pk_bf16_f32 v68, v72, v73
	v_cvt_pk_bf16_f32 v69, v92, v93
	v_exp_f32_e32 v72, v78
	v_sub_f32_e32 v73, v79, v223
	v_mfma_f32_32x32x16_bf16 v[50:65], v[158:161], v[66:69], v[50:65]
	v_exp_f32_e32 v74, v73
	v_sub_f32_e32 v76, v80, v223
	v_exp_f32_e32 v76, v76
	v_sub_f32_e32 v77, v81, v223
	v_mfma_f32_32x32x16_bf16 v[34:49], v[154:157], v[66:69], v[34:49]
	v_cvt_pk_bf16_f32 v66, v202, v205
	v_cvt_pk_bf16_f32 v67, v213, v217
	v_cvt_pk_bf16_f32 v68, v84, v85
	v_cvt_pk_bf16_f32 v69, v86, v87
	v_exp_f32_e32 v78, v77
	v_mov_b32_e32 v73, v72
	v_mfma_f32_32x32x16_bf16 v[50:65], v[150:153], v[66:69], v[50:65]
	v_mov_b32_e32 v72, v74
	v_pk_mov_b32 v[74:75], v[72:73], v[72:73] op_sel:[1,0]
	v_pk_add_f32 v[70:71], v[70:71], v[72:73]
	v_mov_b32_e32 v77, v76
	v_mfma_f32_32x32x16_bf16 v[34:49], v[146:149], v[66:69], v[34:49]
	v_cvt_pk_bf16_f32 v66, v88, v89
	v_cvt_pk_bf16_f32 v67, v90, v91
	v_mov_b32_e32 v76, v78
	v_pk_mov_b32 v[78:79], v[76:77], v[76:77] op_sel:[1,0]
	v_cvt_pk_bf16_f32 v68, v74, v75
	v_cvt_pk_bf16_f32 v69, v78, v79
	v_add_f32_e32 v71, v71, v218
	v_add_f32_e32 v72, v70, v71
	v_mfma_f32_32x32x16_bf16 v[50:65], v[142:145], v[66:69], v[50:65]
	v_add_f32_e64 v70, v82, v76
	v_add_f32_e64 v71, v83, v77
	v_add_f32_e32 v71, v71, v72
	v_add_f32_e32 v70, v70, v71
	v_add_f32_e32 v228, v228, v70
	v_mfma_f32_32x32x16_bf16 v[34:49], v[138:141], v[66:69], v[34:49]
.LBB0_379:
	s_cmp_lt_u32 s24, s22
	s_cselect_b64 s[30:31], -1, 0
	s_cmp_gt_u32 s27, s23
	s_cselect_b64 s[38:39], -1, 0
	s_or_b64 s[30:31], s[30:31], s[38:39]
	s_and_b64 vcc, exec, s[30:31]
	s_cbranch_vccnz .LBB0_381
	s_sub_i32 s30, s27, s22
	s_sub_i32 s30, s30, 31
	s_cmp_le_u32 s30, 0xa2
	s_cbranch_scc1 .Lswa_fast1
	v_mfma_f32_32x32x16_bf16 v[82:97], v[194:197], v[114:117], 0
	v_mfma_f32_32x32x16_bf16 v[66:81], v[198:201], v[114:117], 0
	v_mfma_f32_32x32x16_bf16 v[82:97], v[190:193], v[118:121], v[82:97]
	v_mfma_f32_32x32x16_bf16 v[66:81], v[186:189], v[118:121], v[66:81]
	v_mfma_f32_32x32x16_bf16 v[82:97], v[182:185], v[122:125], v[82:97]
	v_mfma_f32_32x32x16_bf16 v[66:81], v[178:181], v[122:125], v[66:81]
	v_mfma_f32_32x32x16_bf16 v[82:97], v[174:177], v[126:129], v[82:97]
	v_add_u32_e32 v174, 0xffffffa1, v233
	v_cmp_gt_u32_e32 vcc, s96, v174
	v_mfma_f32_32x32x16_bf16 v[66:81], v[170:173], v[126:129], v[66:81]
	s_nop 8
	v_sub_f32_e32 v82, v82, v223
	v_exp_f32_e32 v82, v82
	v_sub_f32_e32 v83, v83, v223
	v_exp_f32_e32 v83, v83
	v_sub_f32_e32 v96, v96, v223
	v_cndmask_b32_e32 v170, 0, v82, vcc
	v_cmp_gt_u32_e32 vcc, s96, v245
	v_sub_f32_e32 v66, v66, v223
	v_exp_f32_e32 v66, v66
	v_sub_f32_e32 v67, v67, v223
	v_exp_f32_e32 v67, v67
	v_add_u32_e32 v82, 0xffffffa2, v233
	v_cndmask_b32_e32 v171, 0, v66, vcc
	v_cmp_gt_u32_e32 vcc, s96, v82
	v_sub_f32_e32 v82, v84, v223
	v_add_f32_e32 v66, v170, v171
	v_cndmask_b32_e32 v172, 0, v83, vcc
	v_cmp_gt_u32_e32 vcc, s96, v244
	v_exp_f32_e32 v82, v82
	v_sub_f32_e32 v68, v68, v223
	v_cndmask_b32_e32 v173, 0, v67, vcc
	v_add_f32_e32 v66, 0, v66
	v_add_f32_e32 v67, v172, v173
	v_exp_f32_e32 v68, v68
	v_add_f32_e32 v66, v67, v66
	v_add_u32_e32 v67, 0xffffffa3, v233
	v_cmp_gt_u32_e32 vcc, s96, v67
	v_sub_f32_e32 v69, v69, v223
	v_exp_f32_e32 v69, v69
	v_cndmask_b32_e32 v174, 0, v82, vcc
	v_cmp_gt_u32_e32 vcc, s96, v243
	s_nop 1
	v_cndmask_b32_e32 v175, 0, v68, vcc
	v_sub_f32_e32 v68, v85, v223
	v_exp_f32_e32 v68, v68
	v_add_f32_e32 v67, v174, v175
	v_add_f32_e32 v66, v67, v66
	v_add_u32_e32 v67, 0xffffffa4, v233
	v_cmp_gt_u32_e32 vcc, s96, v67
	s_nop 1
	v_cndmask_b32_e32 v176, 0, v68, vcc
	v_cmp_gt_u32_e32 vcc, s96, v242
	s_nop 1
	v_cndmask_b32_e32 v177, 0, v69, vcc
	v_add_f32_e32 v67, v176, v177
	v_add_f32_e32 v82, v67, v66
	v_sub_f32_e32 v66, v86, v223
	v_sub_f32_e32 v67, v70, v223
	v_exp_f32_e32 v66, v66
	v_exp_f32_e32 v68, v67
	v_sub_f32_e32 v67, v87, v223
	v_exp_f32_e32 v69, v67
	v_sub_f32_e32 v67, v71, v223
	v_exp_f32_e32 v70, v67
	v_add_u32_e32 v67, 0xffffffa9, v233
	v_add_u32_e32 v71, 0xffffffaa, v233
	v_cmp_gt_u32_e32 vcc, s96, v67
	s_nop 1
	v_cndmask_b32_e32 v67, 0, v66, vcc
	v_cmp_gt_u32_e32 vcc, s96, v71
	s_nop 1
	v_cndmask_b32_e32 v66, 0, v69, vcc
	v_cmp_gt_u32_e32 vcc, s96, v241
	s_nop 1
	v_cndmask_b32_e32 v69, 0, v68, vcc
	v_cmp_gt_u32_e32 vcc, s96, v240
	s_nop 1
	v_cndmask_b32_e32 v68, 0, v70, vcc
	v_pk_add_f32 v[70:71], v[66:67], v[68:69]
	v_pk_mov_b32 v[84:85], v[68:69], v[68:69] op_sel:[1,0]
	v_add_f32_e32 v71, v71, v82
	v_pk_mov_b32 v[82:83], v[66:67], v[66:67] op_sel:[1,0]
	v_sub_f32_e32 v66, v88, v223
	v_sub_f32_e32 v67, v72, v223
	v_exp_f32_e32 v66, v66
	v_exp_f32_e32 v68, v67
	v_sub_f32_e32 v67, v89, v223
	v_exp_f32_e32 v69, v67
	v_sub_f32_e32 v67, v73, v223
	v_add_f32_e32 v86, v70, v71
	v_exp_f32_e32 v70, v67
	v_add_u32_e32 v67, 0xffffffab, v233
	v_add_u32_e32 v71, 0xffffffac, v233
	v_cmp_gt_u32_e32 vcc, s96, v67
	s_nop 1
	v_cndmask_b32_e32 v67, 0, v66, vcc
	v_cmp_gt_u32_e32 vcc, s96, v71
	s_nop 1
	v_cndmask_b32_e32 v66, 0, v69, vcc
	v_cmp_gt_u32_e32 vcc, s96, v239
	v_pk_mov_b32 v[72:73], v[66:67], v[66:67] op_sel:[1,0]
	s_nop 0
	v_cndmask_b32_e32 v69, 0, v68, vcc
	v_cmp_gt_u32_e32 vcc, s96, v238
	s_nop 1
	v_cndmask_b32_e32 v68, 0, v70, vcc
	v_pk_add_f32 v[70:71], v[66:67], v[68:69]
	v_sub_f32_e32 v66, v90, v223
	v_sub_f32_e32 v67, v74, v223
	v_add_f32_e32 v71, v71, v86
	v_pk_mov_b32 v[86:87], v[68:69], v[68:69] op_sel:[1,0]
	v_exp_f32_e32 v66, v66
	v_exp_f32_e32 v68, v67
	v_sub_f32_e32 v67, v91, v223
	v_exp_f32_e32 v69, v67
	v_sub_f32_e32 v67, v75, v223
	v_add_f32_e32 v88, v70, v71
	v_exp_f32_e32 v70, v67
	v_add_u32_e32 v67, 0xffffffb1, v233
	v_add_u32_e32 v71, 0xffffffb2, v233
	v_cmp_gt_u32_e32 vcc, s96, v67
	s_nop 1
	v_cndmask_b32_e32 v67, 0, v66, vcc
	v_cmp_gt_u32_e32 vcc, s96, v71
	s_nop 1
	v_cndmask_b32_e32 v66, 0, v69, vcc
	v_cmp_gt_u32_e32 vcc, s96, v237
	v_pk_mov_b32 v[74:75], v[66:67], v[66:67] op_sel:[1,0]
	s_nop 0
	v_cndmask_b32_e32 v69, 0, v68, vcc
	v_cmp_gt_u32_e32 vcc, s96, v236
	s_nop 1
	v_cndmask_b32_e32 v68, 0, v70, vcc
	v_pk_add_f32 v[70:71], v[66:67], v[68:69]
	v_sub_f32_e32 v66, v92, v223
	v_sub_f32_e32 v67, v76, v223
	v_add_f32_e32 v71, v71, v88
	v_pk_mov_b32 v[88:89], v[68:69], v[68:69] op_sel:[1,0]
	v_exp_f32_e32 v66, v66
	v_exp_f32_e32 v68, v67
	v_sub_f32_e32 v67, v93, v223
	v_exp_f32_e32 v69, v67
	v_sub_f32_e32 v67, v77, v223
	v_add_f32_e32 v178, v70, v71
	v_exp_f32_e32 v70, v67
	v_add_u32_e32 v67, 0xffffffb3, v233
	v_add_u32_e32 v71, 0xffffffb4, v233
	v_cmp_gt_u32_e32 vcc, s96, v67
	s_nop 1
	v_cndmask_b32_e32 v67, 0, v66, vcc
	v_cmp_gt_u32_e32 vcc, s96, v71
	s_nop 1
	v_cndmask_b32_e32 v66, 0, v69, vcc
	v_cmp_gt_u32_e32 vcc, s96, v235
	v_pk_mov_b32 v[90:91], v[66:67], v[66:67] op_sel:[1,0]
	v_add_u32_e32 v69, 0xffffffba, v233
	v_cndmask_b32_e32 v71, 0, v68, vcc
	v_cmp_gt_u32_e32 vcc, s96, v234
	v_add_u32_e32 v68, 0xffffffb9, v233
	s_nop 0
	v_cndmask_b32_e32 v70, 0, v70, vcc
	v_pk_add_f32 v[76:77], v[66:67], v[70:71]
	v_sub_f32_e32 v66, v94, v223
	v_exp_f32_e32 v66, v66
	v_sub_f32_e32 v67, v95, v223
	v_exp_f32_e32 v67, v67
	v_cmp_gt_u32_e32 vcc, s96, v68
	v_cvt_pk_bf16_f32 v68, v82, v83
	v_add_u32_e32 v83, 0xffffffbc, v233
	v_cndmask_b32_e32 v93, 0, v66, vcc
	v_cmp_gt_u32_e32 vcc, s96, v69
	v_cvt_pk_bf16_f32 v66, v170, v172
	v_cvt_pk_bf16_f32 v69, v72, v73
	v_cndmask_b32_e32 v92, 0, v67, vcc
	v_cvt_pk_bf16_f32 v67, v174, v176
	v_exp_f32_e32 v72, v96
	v_sub_f32_e32 v73, v97, v223
	v_mfma_f32_32x32x16_bf16 v[18:33], v[166:169], v[66:69], v[18:33]
	v_exp_f32_e32 v82, v73
	v_add_u32_e32 v73, 0xffffffbb, v233
	v_cmp_gt_u32_e32 vcc, s96, v73
	v_pk_mov_b32 v[94:95], v[92:93], v[92:93] op_sel:[1,0]
	v_pk_mov_b32 v[70:71], v[70:71], v[70:71] op_sel:[1,0]
	v_cndmask_b32_e32 v73, 0, v72, vcc
	v_cmp_gt_u32_e32 vcc, s96, v83
	v_mfma_f32_32x32x16_bf16 v[2:17], v[162:165], v[66:69], v[2:17]
	v_cvt_pk_bf16_f32 v66, v74, v75
	v_cndmask_b32_e32 v72, 0, v82, vcc
	v_pk_mov_b32 v[82:83], v[72:73], v[72:73] op_sel:[1,0]
	v_cvt_pk_bf16_f32 v67, v90, v91
	v_cvt_pk_bf16_f32 v68, v94, v95
	v_cvt_pk_bf16_f32 v69, v82, v83
	v_add_f32_e32 v74, v77, v178
	v_add_f32_e32 v82, v76, v74
	v_mfma_f32_32x32x16_bf16 v[18:33], v[158:161], v[66:69], v[18:33]
	v_sub_f32_e32 v74, v78, v223
	v_exp_f32_e32 v74, v74
	v_sub_f32_e32 v75, v79, v223
	v_exp_f32_e32 v76, v75
	v_sub_f32_e32 v78, v80, v223
	v_exp_f32_e32 v78, v78
	v_sub_f32_e32 v79, v81, v223
	v_mfma_f32_32x32x16_bf16 v[2:17], v[154:157], v[66:69], v[2:17]
	v_cvt_pk_bf16_f32 v66, v171, v173
	v_cvt_pk_bf16_f32 v67, v175, v177
	v_cvt_pk_bf16_f32 v68, v84, v85
	v_cvt_pk_bf16_f32 v69, v86, v87
	v_cmp_gt_u32_e32 vcc, s96, v232
	v_exp_f32_e32 v80, v79
	v_mfma_f32_32x32x16_bf16 v[18:33], v[150:153], v[66:69], v[18:33]
	v_cndmask_b32_e32 v75, 0, v74, vcc
	v_cmp_gt_u32_e32 vcc, s96, v231
	s_nop 1
	v_cndmask_b32_e32 v74, 0, v76, vcc
	v_cmp_gt_u32_e32 vcc, s96, v230
	v_pk_mov_b32 v[76:77], v[74:75], v[74:75] op_sel:[1,0]
	v_mfma_f32_32x32x16_bf16 v[2:17], v[146:149], v[66:69], v[2:17]
	v_cndmask_b32_e32 v79, 0, v78, vcc
	v_cmp_gt_u32_e32 vcc, s96, v0
	v_cvt_pk_bf16_f32 v66, v88, v89
	v_cvt_pk_bf16_f32 v67, v70, v71
	v_cndmask_b32_e32 v78, 0, v80, vcc
	v_pk_mov_b32 v[80:81], v[78:79], v[78:79] op_sel:[1,0]
	v_cvt_pk_bf16_f32 v68, v76, v77
	v_cvt_pk_bf16_f32 v69, v80, v81
	v_pk_add_f32 v[70:71], v[92:93], v[74:75]
	s_nop 0
	v_mfma_f32_32x32x16_bf16 v[18:33], v[142:145], v[66:69], v[18:33]
	v_add_f32_e32 v0, v71, v82
	v_add_f32_e32 v0, v70, v0
	v_add_f32_e64 v70, v72, v78
	v_add_f32_e64 v71, v73, v79
	v_add_f32_e32 v0, v71, v0
	v_add_f32_e32 v0, v70, v0
	v_add_f32_e32 v209, v209, v0
	v_mfma_f32_32x32x16_bf16 v[2:17], v[138:141], v[66:69], v[2:17]
	s_branch .LBB0_381
.Lswa_fast1:
	v_mfma_f32_32x32x16_bf16 v[82:97], v[194:197], v[114:117], 0
	v_mfma_f32_32x32x16_bf16 v[66:81], v[198:201], v[114:117], 0
	v_mfma_f32_32x32x16_bf16 v[82:97], v[190:193], v[118:121], v[82:97]
	v_mfma_f32_32x32x16_bf16 v[66:81], v[186:189], v[118:121], v[66:81]
	v_mfma_f32_32x32x16_bf16 v[82:97], v[182:185], v[122:125], v[82:97]
	v_mfma_f32_32x32x16_bf16 v[66:81], v[178:181], v[122:125], v[66:81]
	v_mfma_f32_32x32x16_bf16 v[82:97], v[174:177], v[126:129], v[82:97]
	v_mfma_f32_32x32x16_bf16 v[66:81], v[170:173], v[126:129], v[66:81]
	s_nop 10
	v_sub_f32_e32 v82, v82, v223
	v_exp_f32_e32 v82, v82
	v_sub_f32_e32 v83, v83, v223
	v_exp_f32_e32 v83, v83
	v_sub_f32_e32 v96, v96, v223
	v_mov_b32_e32 v170, v82
	v_sub_f32_e32 v66, v66, v223
	v_exp_f32_e32 v66, v66
	v_sub_f32_e32 v67, v67, v223
	v_exp_f32_e32 v67, v67
	v_mov_b32_e32 v171, v66
	v_sub_f32_e32 v82, v84, v223
	v_add_f32_e32 v66, v170, v171
	v_mov_b32_e32 v172, v83
	v_exp_f32_e32 v82, v82
	v_sub_f32_e32 v68, v68, v223
	v_mov_b32_e32 v173, v67
	v_add_f32_e32 v66, 0, v66
	v_add_f32_e32 v67, v172, v173
	v_exp_f32_e32 v68, v68
	v_add_f32_e32 v66, v67, v66
	v_sub_f32_e32 v69, v69, v223
	v_exp_f32_e32 v69, v69
	v_mov_b32_e32 v174, v82
	v_mov_b32_e32 v175, v68
	v_sub_f32_e32 v68, v85, v223
	v_exp_f32_e32 v68, v68
	v_add_f32_e32 v67, v174, v175
	v_add_f32_e32 v66, v67, v66
	v_mov_b32_e32 v176, v68
	v_mov_b32_e32 v177, v69
	v_add_f32_e32 v67, v176, v177
	v_add_f32_e32 v82, v67, v66
	v_sub_f32_e32 v66, v86, v223
	v_sub_f32_e32 v67, v70, v223
	v_exp_f32_e32 v66, v66
	v_exp_f32_e32 v68, v67
	v_sub_f32_e32 v67, v87, v223
	v_exp_f32_e32 v69, v67
	v_sub_f32_e32 v67, v71, v223
	v_exp_f32_e32 v70, v67
	v_mov_b32_e32 v67, v66
	v_mov_b32_e32 v66, v69
	v_mov_b32_e32 v69, v68
	v_mov_b32_e32 v68, v70
	v_pk_add_f32 v[70:71], v[66:67], v[68:69]
	v_pk_mov_b32 v[84:85], v[68:69], v[68:69] op_sel:[1,0]
	v_add_f32_e32 v71, v71, v82
	v_pk_mov_b32 v[82:83], v[66:67], v[66:67] op_sel:[1,0]
	v_sub_f32_e32 v66, v88, v223
	v_sub_f32_e32 v67, v72, v223
	v_exp_f32_e32 v66, v66
	v_exp_f32_e32 v68, v67
	v_sub_f32_e32 v67, v89, v223
	v_exp_f32_e32 v69, v67
	v_sub_f32_e32 v67, v73, v223
	v_add_f32_e32 v86, v70, v71
	v_exp_f32_e32 v70, v67
	v_mov_b32_e32 v67, v66
	v_mov_b32_e32 v66, v69
	v_pk_mov_b32 v[72:73], v[66:67], v[66:67] op_sel:[1,0]
	v_mov_b32_e32 v69, v68
	v_mov_b32_e32 v68, v70
	v_pk_add_f32 v[70:71], v[66:67], v[68:69]
	v_sub_f32_e32 v66, v90, v223
	v_sub_f32_e32 v67, v74, v223
	v_add_f32_e32 v71, v71, v86
	v_pk_mov_b32 v[86:87], v[68:69], v[68:69] op_sel:[1,0]
	v_exp_f32_e32 v66, v66
	v_exp_f32_e32 v68, v67
	v_sub_f32_e32 v67, v91, v223
	v_exp_f32_e32 v69, v67
	v_sub_f32_e32 v67, v75, v223
	v_add_f32_e32 v88, v70, v71
	v_exp_f32_e32 v70, v67
	v_mov_b32_e32 v67, v66
	v_mov_b32_e32 v66, v69
	v_pk_mov_b32 v[74:75], v[66:67], v[66:67] op_sel:[1,0]
	v_mov_b32_e32 v69, v68
	v_mov_b32_e32 v68, v70
	v_pk_add_f32 v[70:71], v[66:67], v[68:69]
	v_sub_f32_e32 v66, v92, v223
	v_sub_f32_e32 v67, v76, v223
	v_add_f32_e32 v71, v71, v88
	v_pk_mov_b32 v[88:89], v[68:69], v[68:69] op_sel:[1,0]
	v_exp_f32_e32 v66, v66
	v_exp_f32_e32 v68, v67
	v_sub_f32_e32 v67, v93, v223
	v_exp_f32_e32 v69, v67
	v_sub_f32_e32 v67, v77, v223
	v_add_f32_e32 v178, v70, v71
	v_exp_f32_e32 v70, v67
	v_mov_b32_e32 v67, v66
	v_mov_b32_e32 v66, v69
	v_pk_mov_b32 v[90:91], v[66:67], v[66:67] op_sel:[1,0]
	v_mov_b32_e32 v71, v68
	v_mov_b32_e32 v70, v70
	v_pk_add_f32 v[76:77], v[66:67], v[70:71]
	v_sub_f32_e32 v66, v94, v223
	v_exp_f32_e32 v66, v66
	v_sub_f32_e32 v67, v95, v223
	v_exp_f32_e32 v67, v67
	v_cvt_pk_bf16_f32 v68, v82, v83
	v_mov_b32_e32 v93, v66
	v_cvt_pk_bf16_f32 v66, v170, v172
	v_cvt_pk_bf16_f32 v69, v72, v73
	v_mov_b32_e32 v92, v67
	v_cvt_pk_bf16_f32 v67, v174, v176
	v_exp_f32_e32 v72, v96
	v_sub_f32_e32 v73, v97, v223
	v_mfma_f32_32x32x16_bf16 v[18:33], v[166:169], v[66:69], v[18:33]
	v_exp_f32_e32 v82, v73
	v_pk_mov_b32 v[94:95], v[92:93], v[92:93] op_sel:[1,0]
	v_pk_mov_b32 v[70:71], v[70:71], v[70:71] op_sel:[1,0]
	v_mov_b32_e32 v73, v72
	v_mfma_f32_32x32x16_bf16 v[2:17], v[162:165], v[66:69], v[2:17]
	v_cvt_pk_bf16_f32 v66, v74, v75
	v_mov_b32_e32 v72, v82
	v_pk_mov_b32 v[82:83], v[72:73], v[72:73] op_sel:[1,0]
	v_cvt_pk_bf16_f32 v67, v90, v91
	v_cvt_pk_bf16_f32 v68, v94, v95
	v_cvt_pk_bf16_f32 v69, v82, v83
	v_add_f32_e32 v74, v77, v178
	v_add_f32_e32 v82, v76, v74
	v_mfma_f32_32x32x16_bf16 v[18:33], v[158:161], v[66:69], v[18:33]
	v_sub_f32_e32 v74, v78, v223
	v_exp_f32_e32 v74, v74
	v_sub_f32_e32 v75, v79, v223
	v_exp_f32_e32 v76, v75
	v_sub_f32_e32 v78, v80, v223
	v_exp_f32_e32 v78, v78
	v_sub_f32_e32 v79, v81, v223
	v_mfma_f32_32x32x16_bf16 v[2:17], v[154:157], v[66:69], v[2:17]
	v_cvt_pk_bf16_f32 v66, v171, v173
	v_cvt_pk_bf16_f32 v67, v175, v177
	v_cvt_pk_bf16_f32 v68, v84, v85
	v_cvt_pk_bf16_f32 v69, v86, v87
	v_exp_f32_e32 v80, v79
	v_mfma_f32_32x32x16_bf16 v[18:33], v[150:153], v[66:69], v[18:33]
	v_mov_b32_e32 v75, v74
	v_mov_b32_e32 v74, v76
	v_pk_mov_b32 v[76:77], v[74:75], v[74:75] op_sel:[1,0]
	v_mfma_f32_32x32x16_bf16 v[2:17], v[146:149], v[66:69], v[2:17]
	v_mov_b32_e32 v79, v78
	v_cvt_pk_bf16_f32 v66, v88, v89
	v_cvt_pk_bf16_f32 v67, v70, v71
	v_mov_b32_e32 v78, v80
	v_pk_mov_b32 v[80:81], v[78:79], v[78:79] op_sel:[1,0]
	v_cvt_pk_bf16_f32 v68, v76, v77
	v_cvt_pk_bf16_f32 v69, v80, v81
	v_pk_add_f32 v[70:71], v[92:93], v[74:75]
	s_nop 0
	v_mfma_f32_32x32x16_bf16 v[18:33], v[142:145], v[66:69], v[18:33]
	v_add_f32_e32 v0, v71, v82
	v_add_f32_e32 v0, v70, v0
	v_add_f32_e64 v70, v72, v78
	v_add_f32_e64 v71, v73, v79
	v_add_f32_e32 v0, v71, v0
	v_add_f32_e32 v0, v70, v0
	v_add_f32_e32 v209, v209, v0
	v_mfma_f32_32x32x16_bf16 v[2:17], v[138:141], v[66:69], v[2:17]
